# attention loop qkt: K fragments prefetched 3 pairs deep into the idle V-fragment registers (counted lgkmcnt) + coalesced cumsum_head loads via LDS; on top of v11
# speedup vs baseline: 1.0058x; 1.0015x over previous
; #define LAS __attribute__((address_space(3)))
; __device__ __forceinline__ void cumsum_head(const float* logf, float* cs, int h, LAS float* sm, int tid) {
;     const int lane = tid & 63, wave = tid >> 6;
;     float v[32]; const float* p = logf + (size_t)(32 * tid) * NH + h; float s = 0.f;
; #pragma unroll
;     for (int i = 0; i < 32; ++i) { v[i] = p[i * NH]; }
; #pragma unroll
.LBB0_127:
	v_readlane_b32 s14, v253, 33
	v_readlane_b32 s15, v253, 34
	v_mov_b32_e32 v36, v202
	s_andn2_b64 vcc, exec, s[14:15]
	s_cbranch_vccnz .LBB0_147
	v_readlane_b32 s14, v253, 37
	v_readlane_b32 s15, v253, 38
	v_and_b32_e32 v37, 64, v203
	v_add_u32_e32 v39, -2, v203
	v_lshlrev_b32_e32 v0, 5, v36
	v_lshrrev_b32_e32 v1, 5, v36
	v_add_u32_e32 v1, v1, v36
	v_lshlrev_b32_e32 v34, 2, v1
	v_ashrrev_i32_e32 v1, 31, v0
	v_add_u32_e32 v34, 0x400, v34
	v_mul_u32_u24_e32 v35, 0x84, v36
	v_add_u32_e32 v35, 0x400, v35
	s_nop 1
	global_load_dword v2, v0, s[14:15]
	s_add_u32 s14, s14, 0x4000
	s_addc_u32 s15, s15, 0
	global_load_dword v3, v0, s[14:15]
	s_add_u32 s14, s14, 0x4000
	s_addc_u32 s15, s15, 0
	global_load_dword v4, v0, s[14:15]
	s_add_u32 s14, s14, 0x4000
	s_addc_u32 s15, s15, 0
	global_load_dword v5, v0, s[14:15]
	s_add_u32 s14, s14, 0x4000
	s_addc_u32 s15, s15, 0
	global_load_dword v6, v0, s[14:15]
	s_add_u32 s14, s14, 0x4000
	s_addc_u32 s15, s15, 0
	global_load_dword v7, v0, s[14:15]
	s_add_u32 s14, s14, 0x4000
	s_addc_u32 s15, s15, 0
	global_load_dword v8, v0, s[14:15]
	s_add_u32 s14, s14, 0x4000
	s_addc_u32 s15, s15, 0
	global_load_dword v9, v0, s[14:15]
	s_add_u32 s14, s14, 0x4000
	s_addc_u32 s15, s15, 0
	global_load_dword v10, v0, s[14:15]
	s_add_u32 s14, s14, 0x4000
	s_addc_u32 s15, s15, 0
	global_load_dword v11, v0, s[14:15]
	s_add_u32 s14, s14, 0x4000
	s_addc_u32 s15, s15, 0
	global_load_dword v12, v0, s[14:15]
	s_add_u32 s14, s14, 0x4000
	s_addc_u32 s15, s15, 0
	global_load_dword v13, v0, s[14:15]
	s_add_u32 s14, s14, 0x4000
	s_addc_u32 s15, s15, 0
	global_load_dword v14, v0, s[14:15]
	s_add_u32 s14, s14, 0x4000
	s_addc_u32 s15, s15, 0
	global_load_dword v15, v0, s[14:15]
	s_add_u32 s14, s14, 0x4000
	s_addc_u32 s15, s15, 0
	global_load_dword v16, v0, s[14:15]
	s_add_u32 s14, s14, 0x4000
	s_addc_u32 s15, s15, 0
	global_load_dword v17, v0, s[14:15]
	s_add_u32 s14, s14, 0x4000
	s_addc_u32 s15, s15, 0
	global_load_dword v18, v0, s[14:15]
	s_add_u32 s14, s14, 0x4000
	s_addc_u32 s15, s15, 0
	global_load_dword v19, v0, s[14:15]
	s_add_u32 s14, s14, 0x4000
	s_addc_u32 s15, s15, 0
	global_load_dword v20, v0, s[14:15]
	s_add_u32 s14, s14, 0x4000
	s_addc_u32 s15, s15, 0
	global_load_dword v21, v0, s[14:15]
	s_add_u32 s14, s14, 0x4000
	s_addc_u32 s15, s15, 0
	global_load_dword v22, v0, s[14:15]
	s_add_u32 s14, s14, 0x4000
	s_addc_u32 s15, s15, 0
	global_load_dword v23, v0, s[14:15]
	s_add_u32 s14, s14, 0x4000
	s_addc_u32 s15, s15, 0
	global_load_dword v24, v0, s[14:15]
	s_add_u32 s14, s14, 0x4000
	s_addc_u32 s15, s15, 0
	global_load_dword v25, v0, s[14:15]
	s_add_u32 s14, s14, 0x4000
	s_addc_u32 s15, s15, 0
	global_load_dword v26, v0, s[14:15]
	s_add_u32 s14, s14, 0x4000
	s_addc_u32 s15, s15, 0
	global_load_dword v27, v0, s[14:15]
	s_add_u32 s14, s14, 0x4000
	s_addc_u32 s15, s15, 0
	global_load_dword v28, v0, s[14:15]
	s_add_u32 s14, s14, 0x4000
	s_addc_u32 s15, s15, 0
	global_load_dword v29, v0, s[14:15]
	s_add_u32 s14, s14, 0x4000
	s_addc_u32 s15, s15, 0
	global_load_dword v30, v0, s[14:15]
	s_add_u32 s14, s14, 0x4000
	s_addc_u32 s15, s15, 0
	global_load_dword v31, v0, s[14:15]
	s_add_u32 s14, s14, 0x4000
	s_addc_u32 s15, s15, 0
	global_load_dword v32, v0, s[14:15]
	s_add_u32 s14, s14, 0x4000
	s_addc_u32 s15, s15, 0
	global_load_dword v33, v0, s[14:15]
	s_waitcnt vmcnt(31)
	ds_write_b32 v34, v2
	s_waitcnt vmcnt(30)
	ds_write_b32 v34, v3 offset:2112
	s_waitcnt vmcnt(29)
	ds_write_b32 v34, v4 offset:4224
	s_waitcnt vmcnt(28)
	ds_write_b32 v34, v5 offset:6336
	s_waitcnt vmcnt(27)
	ds_write_b32 v34, v6 offset:8448
	s_waitcnt vmcnt(26)
	ds_write_b32 v34, v7 offset:10560
	s_waitcnt vmcnt(25)
	ds_write_b32 v34, v8 offset:12672
	s_waitcnt vmcnt(24)
	ds_write_b32 v34, v9 offset:14784
	s_waitcnt vmcnt(23)
	ds_write_b32 v34, v10 offset:16896
	s_waitcnt vmcnt(22)
	ds_write_b32 v34, v11 offset:19008
	s_waitcnt vmcnt(21)
	ds_write_b32 v34, v12 offset:21120
	s_waitcnt vmcnt(20)
	ds_write_b32 v34, v13 offset:23232
	s_waitcnt vmcnt(19)
	ds_write_b32 v34, v14 offset:25344
	s_waitcnt vmcnt(18)
	ds_write_b32 v34, v15 offset:27456
	s_waitcnt vmcnt(17)
	ds_write_b32 v34, v16 offset:29568
	s_waitcnt vmcnt(16)
	ds_write_b32 v34, v17 offset:31680
	s_waitcnt vmcnt(15)
	ds_write_b32 v34, v18 offset:33792
	s_waitcnt vmcnt(14)
	ds_write_b32 v34, v19 offset:35904
	s_waitcnt vmcnt(13)
	ds_write_b32 v34, v20 offset:38016
	s_waitcnt vmcnt(12)
	ds_write_b32 v34, v21 offset:40128
	s_waitcnt vmcnt(11)
	ds_write_b32 v34, v22 offset:42240
	s_waitcnt vmcnt(10)
	ds_write_b32 v34, v23 offset:44352
	s_waitcnt vmcnt(9)
	ds_write_b32 v34, v24 offset:46464
	s_waitcnt vmcnt(8)
	ds_write_b32 v34, v25 offset:48576
	s_waitcnt vmcnt(7)
	ds_write_b32 v34, v26 offset:50688
	s_waitcnt vmcnt(6)
	ds_write_b32 v34, v27 offset:52800
	s_waitcnt vmcnt(5)
	ds_write_b32 v34, v28 offset:54912
	s_waitcnt vmcnt(4)
	ds_write_b32 v34, v29 offset:57024
	s_waitcnt vmcnt(3)
	ds_write_b32 v34, v30 offset:59136
	s_waitcnt vmcnt(2)
	ds_write_b32 v34, v31 offset:61248
	s_waitcnt vmcnt(1)
	ds_write_b32 v34, v32 offset:63360
	s_waitcnt vmcnt(0)
	ds_write_b32 v34, v33 offset:65472
	s_waitcnt lgkmcnt(0)
	s_barrier
; __device__ __forceinline__ void cumsum_head(const float* logf, float* cs, int h, LAS float* sm, int tid) {
;     const int lane = tid & 63, wave = tid >> 6;
;     float v[32]; const float* p = logf + (size_t)(32 * tid) * NH + h; float s = 0.f;
; #pragma unroll
;     for (int i = 0; i < 32; ++i) { v[i] = p[i * NH]; }
; #pragma unroll
;     for (int i = 0; i < 32; ++i) { s += v[i]; }
;     float inc = s;
; #pragma unroll
;     for (int o = 1; o < 64; o <<= 1) { const float n = __shfl_up(inc, o); if (lane >= o) inc += n; }
;     if (lane == 63) sm[wave] = inc;
;     __syncthreads();
;     float wp = 0.f;
; #pragma unroll
;     for (int w = 0; w < 8; ++w) wp += (w < wave) ? sm[w] : 0.f;
	ds_read2_b32 v[30:31], v35 offset0:0 offset1:1
	ds_read2_b32 v[32:33], v35 offset0:2 offset1:3
	ds_read2_b32 v[26:27], v35 offset0:4 offset1:5
	ds_read2_b32 v[28:29], v35 offset0:6 offset1:7
	ds_read2_b32 v[22:23], v35 offset0:8 offset1:9
	ds_read2_b32 v[24:25], v35 offset0:10 offset1:11
	ds_read2_b32 v[18:19], v35 offset0:12 offset1:13
	ds_read2_b32 v[20:21], v35 offset0:14 offset1:15
	ds_read2_b32 v[14:15], v35 offset0:16 offset1:17
	ds_read2_b32 v[16:17], v35 offset0:18 offset1:19
	ds_read2_b32 v[10:11], v35 offset0:20 offset1:21
	ds_read2_b32 v[12:13], v35 offset0:22 offset1:23
	ds_read2_b32 v[6:7], v35 offset0:24 offset1:25
	ds_read2_b32 v[8:9], v35 offset0:26 offset1:27
	ds_read2_b32 v[2:3], v35 offset0:28 offset1:29
	ds_read2_b32 v[4:5], v35 offset0:30 offset1:31
	s_waitcnt lgkmcnt(0)
	v_add_u32_e32 v35, -1, v203
	v_cmp_lt_i32_e32 vcc, v35, v37
	v_and_b32_e32 v34, 63, v36
	v_add_u32_e32 v40, -4, v203
	v_cndmask_b32_e32 v35, v35, v203, vcc
	v_lshlrev_b32_e32 v38, 2, v35
	v_cmp_lt_i32_e32 vcc, v39, v37
	s_waitcnt vmcnt(31)
	v_add_f32_e32 v35, 0, v30
	s_waitcnt vmcnt(30)
	v_add_f32_e32 v35, v35, v31
	s_waitcnt vmcnt(29)
	v_add_f32_e32 v35, v35, v32
	s_waitcnt vmcnt(28)
	v_add_f32_e32 v35, v35, v33
	s_waitcnt vmcnt(27)
	v_add_f32_e32 v35, v35, v26
	s_waitcnt vmcnt(26)
	v_add_f32_e32 v35, v35, v27
	s_waitcnt vmcnt(25)
	v_add_f32_e32 v35, v35, v28
	s_waitcnt vmcnt(24)
	v_add_f32_e32 v35, v35, v29
	s_waitcnt vmcnt(23)
	v_add_f32_e32 v35, v35, v22
	s_waitcnt vmcnt(22)
	v_add_f32_e32 v35, v35, v23
	s_waitcnt vmcnt(21)
	v_add_f32_e32 v35, v35, v24
	s_waitcnt vmcnt(20)
	v_add_f32_e32 v35, v35, v25
	s_waitcnt vmcnt(19)
	v_add_f32_e32 v35, v35, v18
	s_waitcnt vmcnt(18)
	v_add_f32_e32 v35, v35, v19
	s_waitcnt vmcnt(17)
	v_add_f32_e32 v35, v35, v20
	s_waitcnt vmcnt(16)
	v_add_f32_e32 v35, v35, v21
	s_waitcnt vmcnt(15)
	v_add_f32_e32 v35, v35, v14
	s_waitcnt vmcnt(14)
	v_add_f32_e32 v35, v35, v15
	s_waitcnt vmcnt(13)
	v_add_f32_e32 v35, v35, v16
	s_waitcnt vmcnt(12)
	v_add_f32_e32 v35, v35, v17
	s_waitcnt vmcnt(11)
	v_add_f32_e32 v35, v35, v10
	s_waitcnt vmcnt(10)
	v_add_f32_e32 v35, v35, v11
	s_waitcnt vmcnt(9)
	v_add_f32_e32 v35, v35, v12
	s_waitcnt vmcnt(8)
	v_add_f32_e32 v35, v35, v13
	s_waitcnt vmcnt(7)
	v_add_f32_e32 v35, v35, v6
	s_waitcnt vmcnt(6)
	v_add_f32_e32 v35, v35, v7
	s_waitcnt vmcnt(5)
	v_add_f32_e32 v35, v35, v8
	s_waitcnt vmcnt(4)
	v_add_f32_e32 v35, v35, v9
	s_waitcnt vmcnt(3)
	v_add_f32_e32 v35, v35, v2
	s_waitcnt vmcnt(2)
	v_add_f32_e32 v35, v35, v3
	s_waitcnt vmcnt(1)
	v_add_f32_e32 v35, v35, v4
	s_waitcnt vmcnt(0)
	v_add_f32_e32 v35, v35, v5
	ds_bpermute_b32 v38, v38, v35
	v_cndmask_b32_e32 v39, v39, v203, vcc
	v_cmp_eq_u32_e32 vcc, 0, v34
	v_lshlrev_b32_e32 v39, 2, v39
	s_waitcnt lgkmcnt(0)
	v_add_f32_e32 v38, v35, v38
	v_cndmask_b32_e32 v38, v38, v35, vcc
	ds_bpermute_b32 v39, v39, v38
	v_cmp_lt_i32_e32 vcc, v40, v37
	s_waitcnt lgkmcnt(0)
	v_add_f32_e32 v39, v38, v39
	v_cndmask_b32_e32 v40, v40, v203, vcc
	v_cmp_gt_u32_e32 vcc, 2, v34
	v_lshlrev_b32_e32 v40, 2, v40
	s_nop 0
	v_cndmask_b32_e32 v38, v39, v38, vcc
	ds_bpermute_b32 v39, v40, v38
	v_add_u32_e32 v40, -8, v203
	v_cmp_lt_i32_e32 vcc, v40, v37
	s_waitcnt lgkmcnt(0)
	v_add_f32_e32 v39, v38, v39
	v_cndmask_b32_e32 v40, v40, v203, vcc
	v_cmp_gt_u32_e32 vcc, 4, v34
	v_lshlrev_b32_e32 v40, 2, v40
	s_nop 0
	v_cndmask_b32_e32 v38, v39, v38, vcc
	ds_bpermute_b32 v39, v40, v38
	v_add_u32_e32 v40, -16, v203
	v_cmp_lt_i32_e32 vcc, v40, v37
	s_waitcnt lgkmcnt(0)
	v_add_f32_e32 v39, v38, v39
	v_cndmask_b32_e32 v40, v40, v203, vcc
	v_cmp_gt_u32_e32 vcc, 8, v34
	v_lshlrev_b32_e32 v40, 2, v40
	s_nop 0
	v_cndmask_b32_e32 v38, v39, v38, vcc
	ds_bpermute_b32 v39, v40, v38
	v_subrev_u32_e32 v40, 32, v203
	v_cmp_lt_i32_e32 vcc, v40, v37
	s_nop 1
	v_cndmask_b32_e32 v37, v40, v203, vcc
	v_lshlrev_b32_e32 v40, 2, v37
	s_waitcnt lgkmcnt(0)
	v_add_f32_e32 v37, v38, v39
	v_cmp_gt_u32_e32 vcc, 16, v34
	s_nop 1
	v_cndmask_b32_e32 v37, v37, v38, vcc
	ds_bpermute_b32 v39, v40, v37
	v_ashrrev_i32_e32 v38, 6, v36
	v_cmp_eq_u32_e32 vcc, 63, v34
	s_waitcnt lgkmcnt(0)
	v_add_f32_e32 v36, v37, v39
	s_and_saveexec_b64 s[14:15], vcc
	v_lshl_add_u32 v39, v38, 2, 0
	ds_write_b32 v39, v36
	s_or_b64 exec, exec, s[14:15]
	v_cmp_lt_i32_e32 vcc, 0, v38
	v_mov_b32_e32 v39, 0
	v_mov_b32_e32 v40, 0
	s_waitcnt lgkmcnt(0)
	s_barrier
	s_and_saveexec_b64 s[14:15], vcc
	s_cbranch_execz .LBB0_132
	ds_read_b32 v40, v193
	s_waitcnt lgkmcnt(0)
	v_add_f32_e32 v40, 0, v40

; __device__ __forceinline__ void partialSM(f32x16& p0, f32x16& p1, float& m_reg, float& mn, float& alpha) {
;     ...
;     for (int r = 0; r < 16; ++r) p0[r] = __builtin_amdgcn_exp2f(p0[r]);
; }
; __device__ __forceinline__ void finishSM(f32x16& p0, f32x16& p1, float alpha, float& l_reg, bf16x8& pa0, bf16x8& pa1, bf16x8& pa2, bf16x8& pa3) {
;     for (int r = 0; r < 16; ++r) p1[r] = __builtin_amdgcn_exp2f(p1[r]);
;     float ps = 0; for (int r = 0; r < 16; ++r) ps += p0[r]; for (int r = 0; r < 16; ++r) ps += p1[r];
;     { auto rr = __builtin_amdgcn_permlane32_swap(__float_as_uint(ps), __float_as_uint(ps), false, false);
;       ps = __uint_as_float(rr[0]) + __uint_as_float(rr[1]); }
;     l_reg = l_reg * alpha + ps;
;     ...
;     PK4(p0, 0, pa0); PK4(p0, 8, pa1); PK4(p1, 0, pa2); PK4(p1, 8, pa3);
; template <int KB, bool SK>
; __device__ __forceinline__ void qkt(f32x16& p0, f32x16& p1, const char* K_lds, int r32, int hi, const bf16x8* qr, bool act) {
;     ...
;     const char* kb[4];
; #pragma unroll
;     for (int dd = 0; dd < 4; ++dd) kb[dd] = K_lds + KB * SHM_K + KSWZ(r32, (dd * 16 + hi * 8) * 2);
; #pragma unroll
;     for (int d0 = 0; d0 < 8; ++d0) { const char* a = kb[d0 & 3] + (d0 >> 2) * 128;
;         bf16x8 b0 = *reinterpret_cast<const bf16x8*>(a);
;         bf16x8 b1 = *reinterpret_cast<const bf16x8*>(a + 32 * 256);
;         p0 = __builtin_amdgcn_mfma_f32_32x32x16_bf16(b0, qr[d0], p0, 0, 0, 0);
;         p1 = __builtin_amdgcn_mfma_f32_32x32x16_bf16(b1, qr[d0], p1, 0, 0, 0); }
.LBB0_351:
	v_add_u32_e32 v137, s19, v219
	v_add_u32_e32 v64, 1, v137
	v_mad_i64_i32 v[64:65], s[14:15], v64, s85, v[200:201]
	v_add_u32_e32 v66, 33, v137
	v_mad_i64_i32 v[66:67], s[14:15], v66, s85, v[200:201]
	global_load_dwordx4 v[176:179], v[64:65], off offset:2048
	global_load_dwordx4 v[180:183], v[64:65], off
	global_load_dwordx4 v[184:187], v[66:67], off offset:2048
	global_load_dwordx4 v[188:191], v[66:67], off
	ds_read_b128 v[64:67], v224 offset:49152
	ds_read_b128 v[68:71], v224 offset:57344
	ds_read_b128 v[238:241], v223 offset:49152
	ds_read_b128 v[242:245], v223 offset:57344
	ds_read_b128 v[246:249], v222 offset:49152
	ds_read_b128 v[194:197], v222 offset:57344
	v_exp_f32_e32 v72, v124
	v_exp_f32_e32 v73, v125
	v_exp_f32_e32 v74, v122
	s_waitcnt lgkmcnt(5)
	v_mfma_f32_32x32x16_bf16 v[78:93], v[64:67], v[172:175], 0
	v_exp_f32_e32 v75, v123
	v_exp_f32_e32 v76, v120
	v_exp_f32_e32 v77, v121
	v_exp_f32_e32 v118, v118
	v_exp_f32_e32 v119, v119
	v_exp_f32_e32 v116, v116
	v_exp_f32_e32 v117, v117
	s_waitcnt lgkmcnt(4)
	v_mfma_f32_32x32x16_bf16 v[94:109], v[68:71], v[172:175], 0
	ds_read_b128 v[64:67], v221 offset:49152
	ds_read_b128 v[68:71], v221 offset:57344
	v_exp_f32_e32 v114, v114
	v_exp_f32_e32 v115, v115
	v_exp_f32_e32 v112, v112
	v_exp_f32_e32 v113, v113
	v_exp_f32_e32 v120, v110
	v_exp_f32_e32 v121, v111
	s_waitcnt lgkmcnt(5)
	v_mfma_f32_32x32x16_bf16 v[78:93], v[238:241], v[168:171], v[78:93]
	s_sub_i32 s14, s19, 63
	s_waitcnt lgkmcnt(4)
	v_mfma_f32_32x32x16_bf16 v[94:109], v[242:245], v[168:171], v[94:109]
	ds_read_b128 v[238:241], v224 offset:49280
	ds_read_b128 v[242:245], v224 offset:57472
	s_waitcnt lgkmcnt(5)
	v_mfma_f32_32x32x16_bf16 v[78:93], v[246:249], v[164:167], v[78:93]
	s_waitcnt lgkmcnt(4)
	v_mfma_f32_32x32x16_bf16 v[94:109], v[194:197], v[164:167], v[94:109]
	ds_read_b128 v[246:249], v223 offset:49280
	ds_read_b128 v[194:197], v223 offset:57472
	s_waitcnt lgkmcnt(5)
	v_mfma_f32_32x32x16_bf16 v[78:93], v[64:67], v[160:163], v[78:93]
	s_waitcnt lgkmcnt(4)
	v_mfma_f32_32x32x16_bf16 v[94:109], v[68:71], v[160:163], v[94:109]
	ds_read_b128 v[64:67], v222 offset:49280
	ds_read_b128 v[68:71], v222 offset:57472
	s_waitcnt lgkmcnt(5)
	v_mfma_f32_32x32x16_bf16 v[78:93], v[238:241], v[156:159], v[78:93]
	s_waitcnt lgkmcnt(4)
	v_mfma_f32_32x32x16_bf16 v[94:109], v[242:245], v[156:159], v[94:109]
	ds_read_b128 v[238:241], v221 offset:49280
	ds_read_b128 v[242:245], v221 offset:57472
	s_waitcnt lgkmcnt(5)
	v_mfma_f32_32x32x16_bf16 v[78:93], v[246:249], v[152:155], v[78:93]
	s_waitcnt lgkmcnt(4)
	v_mfma_f32_32x32x16_bf16 v[94:109], v[194:197], v[152:155], v[94:109]
	s_waitcnt lgkmcnt(3)
	v_mfma_f32_32x32x16_bf16 v[78:93], v[64:67], v[148:151], v[78:93]
	s_waitcnt lgkmcnt(2)
	v_mfma_f32_32x32x16_bf16 v[94:109], v[68:71], v[148:151], v[94:109]
	s_waitcnt lgkmcnt(1)
	v_mfma_f32_32x32x16_bf16 v[78:93], v[238:241], v[144:147], v[78:93]
	v_add_f32_e32 v64, 0, v141
	v_add_f32_e32 v64, v143, v64
	v_add_f32_e32 v64, v139, v64
	v_add_f32_e32 v64, v142, v64
	v_add_f32_e32 v64, v138, v64
	v_add_f32_e32 v64, v140, v64
	v_add_f32_e32 v64, v135, v64
	v_add_f32_e32 v64, v136, v64
	v_add_f32_e32 v64, v130, v64
	v_add_f32_e32 v64, v133, v64
	v_add_f32_e32 v64, v128, v64
	v_add_f32_e32 v64, v131, v64
	v_add_f32_e32 v64, v126, v64
	v_add_f32_e32 v64, v132, v64
	v_add_f32_e32 v64, v127, v64
	v_add_f32_e32 v64, v129, v64
	v_add_f32_e32 v64, v72, v64
	v_add_f32_e32 v64, v73, v64
	v_add_f32_e32 v64, v74, v64
	v_add_f32_e32 v64, v75, v64
	v_add_f32_e32 v64, v76, v64
	v_add_f32_e32 v64, v77, v64
	v_add_f32_e32 v64, v118, v64
	v_add_f32_e32 v64, v119, v64
	v_add_f32_e32 v64, v116, v64
	v_add_f32_e32 v64, v117, v64
	s_waitcnt lgkmcnt(0)
	v_mfma_f32_32x32x16_bf16 v[94:109], v[242:245], v[144:147], v[94:109]
	v_add_f32_e32 v64, v114, v64
	v_add_f32_e32 v64, v115, v64
	v_add_f32_e32 v64, v112, v64
	v_add_f32_e32 v64, v113, v64
	v_add_f32_e32 v64, v120, v64
	v_add_f32_e32 v231, v121, v64
	v_mov_b32_e32 v232, v231
	v_cvt_pk_bf16_f32 v64, v141, v143
	v_cvt_pk_bf16_f32 v65, v139, v142
	v_cvt_pk_bf16_f32 v66, v138, v140
	v_cvt_pk_bf16_f32 v67, v135, v136
	v_cvt_pk_bf16_f32 v68, v130, v133
	v_cvt_pk_bf16_f32 v69, v128, v131
	v_cvt_pk_bf16_f32 v70, v126, v132
	v_cvt_pk_bf16_f32 v71, v127, v129
	v_cvt_pk_bf16_f32 v72, v72, v73
	v_cvt_pk_bf16_f32 v73, v74, v75
	v_cvt_pk_bf16_f32 v74, v76, v77
	v_cvt_pk_bf16_f32 v75, v118, v119
	s_nop 1
	v_permlane32_swap_b32_e32 v231, v232
	v_permlane32_swap_b32_e32 v64, v66
	v_permlane32_swap_b32_e32 v65, v67
	v_permlane32_swap_b32_e32 v68, v70
	v_permlane32_swap_b32_e32 v69, v71
	v_permlane32_swap_b32_e32 v72, v74
	v_permlane32_swap_b32_e32 v73, v75
	v_cvt_pk_bf16_f32 v110, v116, v117
	v_cvt_pk_bf16_f32 v111, v114, v115
	v_cvt_pk_bf16_f32 v112, v112, v113
	v_cvt_pk_bf16_f32 v113, v120, v121
	s_nop 0
	v_permlane32_swap_b32_e32 v110, v112
	v_permlane32_swap_b32_e32 v111, v113
	ds_read_b64_tr_b16 v[114:115], v216 offset:0
	ds_read_b64_tr_b16 v[116:117], v216 offset:0x800
	ds_read_b64_tr_b16 v[118:119], v216 offset:0x1000
	ds_read_b64_tr_b16 v[120:121], v216 offset:0x1800
	ds_read_b64_tr_b16 v[122:123], v216 offset:0x2000
	ds_read_b64_tr_b16 v[124:125], v216 offset:0x2800
	ds_read_b64_tr_b16 v[126:127], v216 offset:0x3000
	ds_read_b64_tr_b16 v[128:129], v216 offset:0x3800
	s_waitcnt lgkmcnt(0)
; #define SBAR() __builtin_amdgcn_sched_barrier(0)
; __device__ __forceinline__ void bias_tile(f32x16& p0, f32x16& p1, const float* cst, int hi) {
; #pragma unroll
;     for (int i = 0; i < 4; ++i) { const f32x4 a = *(const f32x4*)(cst + 8 * i + 4 * hi);
; #pragma unroll
;         for (int j = 0; j < 4; ++j) p0[4 * i + j] -= a[j]; }
;     SBAR();
; #pragma unroll
;     for (int i = 0; i < 4; ++i) { const f32x4 b = *(const f32x4*)(cst + 32 + 8 * i + 4 * hi);
; #pragma unroll
;         for (int j = 0; j < 4; ++j) p1[4 * i + j] -= b[j]; }
; }
; template <int VB, bool SK>
; __device__ __forceinline__ void pv_tile(f32x16* o, int vb0, bf16x8 pa0, bf16x8 pa1, bf16x8 pa2, bf16x8 pa3, bool act) {
;     if (SK && !act) return;
;     ...
;     PV_D0(0); PV_D0(1); PV_D0(2); PV_D0(3);
	s_nop 0
	v_mfma_f32_32x32x16_bf16 v[48:63], v[64:67], v[114:117], v[48:63]
	ds_read_b64_tr_b16 v[114:115], v216 offset:0x200
	ds_read_b64_tr_b16 v[116:117], v216 offset:0xa00
	v_mfma_f32_32x32x16_bf16 v[48:63], v[68:71], v[118:121], v[48:63]
	ds_read_b64_tr_b16 v[118:119], v216 offset:0x1200
	ds_read_b64_tr_b16 v[120:121], v216 offset:0x1a00
	v_mfma_f32_32x32x16_bf16 v[48:63], v[72:75], v[122:125], v[48:63]
	ds_read_b64_tr_b16 v[122:123], v216 offset:0x2200
	ds_read_b64_tr_b16 v[124:125], v216 offset:0x2a00
	v_mfma_f32_32x32x16_bf16 v[48:63], v[110:113], v[126:129], v[48:63]
	ds_read_b64_tr_b16 v[126:127], v216 offset:0x3200
	ds_read_b64_tr_b16 v[128:129], v216 offset:0x3a00
	s_waitcnt lgkmcnt(0)
	v_mfma_f32_32x32x16_bf16 v[32:47], v[64:67], v[114:117], v[32:47]
	ds_read_b64_tr_b16 v[114:115], v216 offset:0x400
	ds_read_b64_tr_b16 v[116:117], v216 offset:0xc00
	v_mfma_f32_32x32x16_bf16 v[32:47], v[68:71], v[118:121], v[32:47]
	ds_read_b64_tr_b16 v[118:119], v216 offset:0x1400
	ds_read_b64_tr_b16 v[120:121], v216 offset:0x1c00
	v_mfma_f32_32x32x16_bf16 v[32:47], v[72:75], v[122:125], v[32:47]
	ds_read_b64_tr_b16 v[122:123], v216 offset:0x2400
	ds_read_b64_tr_b16 v[124:125], v216 offset:0x2c00
	v_mfma_f32_32x32x16_bf16 v[32:47], v[110:113], v[126:129], v[32:47]
	ds_read_b64_tr_b16 v[126:127], v216 offset:0x3400
	ds_read_b64_tr_b16 v[128:129], v216 offset:0x3c00
	s_waitcnt lgkmcnt(0)
	v_mfma_f32_32x32x16_bf16 v[16:31], v[64:67], v[114:117], v[16:31]
	ds_read_b64_tr_b16 v[114:115], v216 offset:0x600
	ds_read_b64_tr_b16 v[116:117], v216 offset:0xe00
	v_mfma_f32_32x32x16_bf16 v[16:31], v[68:71], v[118:121], v[16:31]
	ds_read_b64_tr_b16 v[118:119], v216 offset:0x1600
	ds_read_b64_tr_b16 v[120:121], v216 offset:0x1e00
	v_mfma_f32_32x32x16_bf16 v[16:31], v[72:75], v[122:125], v[16:31]
	ds_read_b64_tr_b16 v[122:123], v216 offset:0x2600
	ds_read_b64_tr_b16 v[124:125], v216 offset:0x2e00
	v_mfma_f32_32x32x16_bf16 v[16:31], v[110:113], v[126:129], v[16:31]
	ds_read_b64_tr_b16 v[126:127], v216 offset:0x3600
	ds_read_b64_tr_b16 v[128:129], v216 offset:0x3e00
	s_waitcnt lgkmcnt(0)
	v_mfma_f32_32x32x16_bf16 v[0:15], v[64:67], v[114:117], v[0:15]
	v_mfma_f32_32x32x16_bf16 v[0:15], v[68:71], v[118:121], v[0:15]
	v_mfma_f32_32x32x16_bf16 v[0:15], v[72:75], v[122:125], v[0:15]
	v_mfma_f32_32x32x16_bf16 v[0:15], v[110:113], v[126:129], v[0:15]
	ds_read_b128 v[110:113], v229
	ds_read_b128 v[74:77], v229 offset:32
	ds_read_b128 v[70:73], v229 offset:64
	ds_read_b128 v[66:69], v229 offset:96
	s_waitcnt lgkmcnt(3)
	v_sub_f32_e32 v79, v79, v111
	s_waitcnt lgkmcnt(2)
	v_sub_f32_e32 v75, v83, v75
	s_waitcnt lgkmcnt(1)
	v_sub_f32_e32 v71, v87, v71
	s_waitcnt lgkmcnt(0)
	v_sub_f32_e32 v65, v93, v69
	v_sub_f32_e32 v64, v92, v68
	v_sub_f32_e32 v67, v91, v67
	v_sub_f32_e32 v66, v90, v66
	v_sub_f32_e32 v69, v89, v73
	v_sub_f32_e32 v68, v88, v72
	v_sub_f32_e32 v70, v86, v70
	v_sub_f32_e32 v73, v85, v77
	v_sub_f32_e32 v72, v84, v76
	v_sub_f32_e32 v74, v82, v74
	v_sub_f32_e32 v77, v81, v113
	v_sub_f32_e32 v76, v80, v112
	v_sub_f32_e32 v78, v78, v110
	ds_read_b128 v[82:85], v229 offset:224
	ds_read_b128 v[86:89], v229 offset:192
	ds_read_b128 v[110:113], v229 offset:128
	ds_read_b128 v[90:93], v229 offset:160
	s_cmp_le_i32 s19, s59
	s_cselect_b64 s[20:21], -1, 0
	s_cmp_gt_i32 s14, s16
	s_cselect_b64 s[14:15], -1, 0
	s_and_b64 s[14:15], s[20:21], s[14:15]
	s_waitcnt lgkmcnt(3)
	v_sub_f32_e32 v81, v109, v85
	v_sub_f32_e32 v80, v108, v84
	v_sub_f32_e32 v83, v107, v83
	v_sub_f32_e32 v82, v106, v82
	s_waitcnt lgkmcnt(2)
	v_sub_f32_e32 v85, v105, v89
	v_sub_f32_e32 v84, v104, v88
	v_sub_f32_e32 v87, v103, v87
	v_sub_f32_e32 v86, v102, v86
	s_waitcnt lgkmcnt(0)
	v_sub_f32_e32 v89, v101, v93
	v_sub_f32_e32 v88, v100, v92
	v_sub_f32_e32 v91, v99, v91
	v_sub_f32_e32 v90, v98, v90
	v_sub_f32_e32 v93, v97, v113
	v_sub_f32_e32 v92, v96, v112
	v_sub_f32_e32 v95, v95, v111
	v_sub_f32_e32 v94, v94, v110
	s_and_b64 vcc, exec, s[14:15]
	s_cbranch_vccnz .LBB0_353
; __device__ __forceinline__ void mask_tile(f32x16& p0, f32x16& p1, int dq, unsigned W) {
;     const float NEG = -__builtin_inff();
; #pragma unroll
;     for (int r = 0; r < 16; ++r) {
;         const int c = (r & 3) + 8 * (r >> 2);
;         if ((unsigned)(dq - c) >= W) p0[r] = NEG;
;         if ((unsigned)(dq - c - 32) >= W) p1[r] = NEG;
;     }
; }
	v_add_u32_e32 v96, 0x407b, v230
	v_cmp_gt_u32_e32 vcc, s61, v96
	v_add_u32_e32 v96, 0x5b, v230
	s_nop 0
	v_cndmask_b32_e32 v78, v207, v78, vcc
	v_cmp_lt_u32_e32 vcc, s39, v96
	v_add_u32_e32 v96, 0x7a, v230
	s_nop 0
	v_cndmask_b32_e32 v94, v207, v94, vcc
	v_cmp_lt_u32_e32 vcc, s39, v96
	v_add_u32_e32 v96, 0x5a, v230
	s_nop 0
	v_cndmask_b32_e32 v79, v207, v79, vcc
	v_cmp_lt_u32_e32 vcc, s39, v96
	v_add_u32_e32 v96, 0x79, v230
	s_nop 0
	v_cndmask_b32_e32 v95, v207, v95, vcc
	v_cmp_lt_u32_e32 vcc, s39, v96
	v_add_u32_e32 v96, 0x59, v230
	s_nop 0
	v_cndmask_b32_e32 v76, v207, v76, vcc
	v_cmp_lt_u32_e32 vcc, s39, v96
	v_add_u32_e32 v96, 0x78, v230
	s_nop 0
	v_cndmask_b32_e32 v92, v207, v92, vcc
	v_cmp_lt_u32_e32 vcc, s39, v96
	v_add_u32_e32 v96, 0x58, v230
	s_nop 0
	v_cndmask_b32_e32 v77, v207, v77, vcc
	v_cmp_lt_u32_e32 vcc, s39, v96
	v_add_u32_e32 v96, 0x73, v230
	s_nop 0
	v_cndmask_b32_e32 v93, v207, v93, vcc
	v_cmp_lt_u32_e32 vcc, s39, v96
	v_add_u32_e32 v96, 0x53, v230
	s_nop 0
	v_cndmask_b32_e32 v74, v207, v74, vcc
	v_cmp_lt_u32_e32 vcc, s39, v96
	v_add_u32_e32 v96, 0x72, v230
	s_nop 0
	v_cndmask_b32_e32 v90, v207, v90, vcc
	v_cmp_lt_u32_e32 vcc, s39, v96
	v_add_u32_e32 v96, 0x52, v230
	s_nop 0
	v_cndmask_b32_e32 v75, v207, v75, vcc
	v_cmp_lt_u32_e32 vcc, s39, v96
	v_add_u32_e32 v96, 0x71, v230
	s_nop 0
	v_cndmask_b32_e32 v91, v207, v91, vcc
	v_cmp_lt_u32_e32 vcc, s39, v96
	v_add_u32_e32 v96, 0x51, v230
	s_nop 0
	v_cndmask_b32_e32 v72, v207, v72, vcc
	v_cmp_lt_u32_e32 vcc, s39, v96
	v_add_u32_e32 v96, 0x70, v230
	s_nop 0
	v_cndmask_b32_e32 v88, v207, v88, vcc
	v_cmp_lt_u32_e32 vcc, s39, v96
	v_add_u32_e32 v96, 0x50, v230
	s_nop 0
	v_cndmask_b32_e32 v73, v207, v73, vcc
	v_cmp_lt_u32_e32 vcc, s39, v96
	v_add_u32_e32 v96, 0x6b, v230
	s_nop 0
	v_cndmask_b32_e32 v89, v207, v89, vcc
	v_cmp_lt_u32_e32 vcc, s39, v96
	v_add_u32_e32 v96, 0x4b, v230
	s_nop 0
	v_cndmask_b32_e32 v70, v207, v70, vcc
	v_cmp_lt_u32_e32 vcc, s39, v96
	v_add_u32_e32 v96, 0x6a, v230
	s_nop 0
	v_cndmask_b32_e32 v86, v207, v86, vcc
	v_cmp_lt_u32_e32 vcc, s39, v96
	v_add_u32_e32 v96, 0x4a, v230
	s_nop 0
	v_cndmask_b32_e32 v71, v207, v71, vcc
	v_cmp_lt_u32_e32 vcc, s39, v96
	v_add_u32_e32 v96, 0x69, v230
	s_nop 0
	v_cndmask_b32_e32 v87, v207, v87, vcc
	v_cmp_lt_u32_e32 vcc, s39, v96
	v_add_u32_e32 v96, 0x49, v230
	s_nop 0
	v_cndmask_b32_e32 v68, v207, v68, vcc
	v_cmp_lt_u32_e32 vcc, s39, v96
	v_add_u32_e32 v96, 0x68, v230
	s_nop 0
	v_cndmask_b32_e32 v84, v207, v84, vcc
	v_cmp_lt_u32_e32 vcc, s39, v96
	v_add_u32_e32 v96, 0x48, v230
	s_nop 0
	v_cndmask_b32_e32 v69, v207, v69, vcc
	v_cmp_lt_u32_e32 vcc, s39, v96
	v_add_u32_e32 v96, 0x63, v230
	s_nop 0
	v_cndmask_b32_e32 v85, v207, v85, vcc
	v_cmp_lt_u32_e32 vcc, s39, v96
	v_add_u32_e32 v96, 0x43, v230
	s_nop 0
	v_cndmask_b32_e32 v66, v207, v66, vcc
	v_cmp_lt_u32_e32 vcc, s39, v96
	v_add_u32_e32 v96, 0x62, v230
	s_nop 0
	v_cndmask_b32_e32 v82, v207, v82, vcc
	v_cmp_lt_u32_e32 vcc, s39, v96
	v_add_u32_e32 v96, 0x42, v230
	s_nop 0
	v_cndmask_b32_e32 v67, v207, v67, vcc
	v_cmp_lt_u32_e32 vcc, s39, v96
	v_add_u32_e32 v96, 0x61, v230
	s_nop 0
	v_cndmask_b32_e32 v83, v207, v83, vcc
	v_cmp_lt_u32_e32 vcc, s39, v96
	v_add_u32_e32 v96, 0x41, v230
	s_nop 0
	v_cndmask_b32_e32 v64, v207, v64, vcc
	v_cmp_lt_u32_e32 vcc, s39, v96
	v_add_u32_e32 v96, 0x60, v230
	s_nop 0
	v_cndmask_b32_e32 v80, v207, v80, vcc
	v_cmp_lt_u32_e32 vcc, s39, v96
	v_add_u32_e32 v96, 64, v230
	s_nop 0
	v_cndmask_b32_e32 v65, v207, v65, vcc
	v_cmp_lt_u32_e32 vcc, s39, v96
	s_nop 1
	v_cndmask_b32_e32 v81, v207, v81, vcc

; __device__ __forceinline__ void finishSM(f32x16& p0, f32x16& p1, float alpha, float& l_reg, bf16x8& pa0, bf16x8& pa1, bf16x8& pa2, bf16x8& pa3) {
;     for (int r = 0; r < 16; ++r) p1[r] = __builtin_amdgcn_exp2f(p1[r]);
;     float ps = 0; for (int r = 0; r < 16; ++r) ps += p0[r]; for (int r = 0; r < 16; ++r) ps += p1[r];
;     { auto rr = __builtin_amdgcn_permlane32_swap(__float_as_uint(ps), __float_as_uint(ps), false, false);
;       ps = __uint_as_float(rr[0]) + __uint_as_float(rr[1]); }
;     l_reg = l_reg * alpha + ps;
;     ...
;     PK4(p0, 0, pa0); PK4(p0, 8, pa1); PK4(p1, 0, pa2); PK4(p1, 8, pa3);
; template <int KB, bool SK>
; __device__ __forceinline__ void qkt(f32x16& p0, f32x16& p1, const char* K_lds, int r32, int hi, const bf16x8* qr, bool act) {
;     ...
;     const char* kb[4];
; #pragma unroll
;     for (int dd = 0; dd < 4; ++dd) kb[dd] = K_lds + KB * SHM_K + KSWZ(r32, (dd * 16 + hi * 8) * 2);
; #pragma unroll
;     for (int d0 = 0; d0 < 8; ++d0) { const char* a = kb[d0 & 3] + (d0 >> 2) * 128;
;         bf16x8 b0 = *reinterpret_cast<const bf16x8*>(a);
;         bf16x8 b1 = *reinterpret_cast<const bf16x8*>(a + 32 * 256);
;         p0 = __builtin_amdgcn_mfma_f32_32x32x16_bf16(b0, qr[d0], p0, 0, 0, 0);
;         p1 = __builtin_amdgcn_mfma_f32_32x32x16_bf16(b1, qr[d0], p1, 0, 0, 0); }
.LBB0_359:
	ds_read_b128 v[80:83], v224 offset:32768
	ds_read_b128 v[84:87], v224 offset:40960
	ds_read_b128 v[238:241], v223 offset:32768
	ds_read_b128 v[242:245], v223 offset:40960
	ds_read_b128 v[246:249], v222 offset:32768
	ds_read_b128 v[194:197], v222 offset:40960
	v_exp_f32_e32 v92, v92
	s_waitcnt lgkmcnt(5)
	v_mfma_f32_32x32x16_bf16 v[128:143], v[80:83], v[172:175], 0
	s_waitcnt lgkmcnt(4)
	v_mfma_f32_32x32x16_bf16 v[112:127], v[84:87], v[172:175], 0
	ds_read_b128 v[80:83], v221 offset:32768
	ds_read_b128 v[84:87], v221 offset:40960
	s_waitcnt lgkmcnt(4)
	v_mfma_f32_32x32x16_bf16 v[112:127], v[242:245], v[168:171], v[112:127]
	v_mfma_f32_32x32x16_bf16 v[128:143], v[238:241], v[168:171], v[128:143]
	ds_read_b128 v[238:241], v224 offset:32896
	ds_read_b128 v[242:245], v224 offset:41088
	s_waitcnt lgkmcnt(4)
	v_mfma_f32_32x32x16_bf16 v[112:127], v[194:197], v[164:167], v[112:127]
	v_mfma_f32_32x32x16_bf16 v[128:143], v[246:249], v[164:167], v[128:143]
	ds_read_b128 v[246:249], v223 offset:32896
	ds_read_b128 v[194:197], v223 offset:41088
	s_waitcnt lgkmcnt(4)
	v_mfma_f32_32x32x16_bf16 v[112:127], v[84:87], v[160:163], v[112:127]
	v_mfma_f32_32x32x16_bf16 v[128:143], v[80:83], v[160:163], v[128:143]
	ds_read_b128 v[80:83], v222 offset:32896
	ds_read_b128 v[84:87], v222 offset:41088
	s_waitcnt lgkmcnt(4)
	v_mfma_f32_32x32x16_bf16 v[112:127], v[242:245], v[156:159], v[112:127]
	v_mfma_f32_32x32x16_bf16 v[128:143], v[238:241], v[156:159], v[128:143]
	ds_read_b128 v[238:241], v221 offset:32896
	ds_read_b128 v[242:245], v221 offset:41088
	s_waitcnt lgkmcnt(4)
	v_mfma_f32_32x32x16_bf16 v[112:127], v[194:197], v[152:155], v[112:127]
	v_mfma_f32_32x32x16_bf16 v[128:143], v[246:249], v[152:155], v[128:143]
	s_waitcnt lgkmcnt(2)
	v_mfma_f32_32x32x16_bf16 v[112:127], v[84:87], v[148:151], v[112:127]
	v_mfma_f32_32x32x16_bf16 v[128:143], v[80:83], v[148:151], v[128:143]
	s_waitcnt lgkmcnt(0)
	v_mfma_f32_32x32x16_bf16 v[112:127], v[242:245], v[144:147], v[112:127]
	v_exp_f32_e32 v86, v88
	v_exp_f32_e32 v88, v91
	v_exp_f32_e32 v91, v95
	v_exp_f32_e32 v95, v96
	v_add_f32_e32 v96, 0, v64
	v_add_f32_e32 v96, v65, v96
	v_add_f32_e32 v96, v66, v96
	v_add_f32_e32 v96, v67, v96
	v_add_f32_e32 v96, v68, v96
	v_add_f32_e32 v96, v69, v96
	v_add_f32_e32 v96, v70, v96
	v_add_f32_e32 v96, v71, v96
	v_add_f32_e32 v96, v72, v96
	v_add_f32_e32 v96, v73, v96
	v_add_f32_e32 v96, v74, v96
	v_add_f32_e32 v96, v75, v96
	v_mfma_f32_32x32x16_bf16 v[128:143], v[238:241], v[144:147], v[128:143]
	v_exp_f32_e32 v80, v97
	v_add_f32_e32 v96, v76, v96
	v_exp_f32_e32 v81, v98
	v_add_f32_e32 v96, v77, v96
	v_exp_f32_e32 v82, v99
	v_add_f32_e32 v96, v78, v96
	v_exp_f32_e32 v83, v100
	v_add_f32_e32 v96, v79, v96
	v_exp_f32_e32 v84, v101
	v_add_f32_e32 v96, v80, v96
	v_exp_f32_e32 v85, v90
	v_add_f32_e32 v96, v81, v96
	v_add_f32_e32 v96, v82, v96
	v_exp_f32_e32 v87, v89
	v_add_f32_e32 v96, v83, v96
	v_add_f32_e32 v96, v84, v96
	v_exp_f32_e32 v89, v93
	v_add_f32_e32 v96, v85, v96
	v_exp_f32_e32 v90, v94
	v_add_f32_e32 v96, v86, v96
	v_add_f32_e32 v96, v87, v96
	v_add_f32_e32 v96, v88, v96
	v_exp_f32_e32 v93, v102
	v_add_f32_e32 v96, v89, v96
	v_exp_f32_e32 v94, v103
	v_add_f32_e32 v96, v90, v96
	v_add_f32_e32 v96, v91, v96
	v_add_f32_e32 v96, v92, v96
	v_add_f32_e32 v96, v93, v96
	v_add_f32_e32 v96, v94, v96
	v_add_f32_e32 v235, v95, v96
	v_mov_b32_e32 v236, v235
	v_cvt_pk_bf16_f32 v96, v64, v65
	v_cvt_pk_bf16_f32 v97, v66, v67
	v_cvt_pk_bf16_f32 v98, v68, v69
	v_cvt_pk_bf16_f32 v99, v70, v71
	v_cvt_pk_bf16_f32 v100, v72, v73
	v_cvt_pk_bf16_f32 v101, v74, v75
	v_cvt_pk_bf16_f32 v102, v76, v77
	v_cvt_pk_bf16_f32 v103, v78, v79
	v_cvt_pk_bf16_f32 v104, v80, v81
	v_cvt_pk_bf16_f32 v105, v82, v83
	v_cvt_pk_bf16_f32 v106, v84, v85
	v_cvt_pk_bf16_f32 v107, v86, v87
	v_cvt_pk_bf16_f32 v108, v88, v89
	v_cvt_pk_bf16_f32 v109, v90, v91
	v_cvt_pk_bf16_f32 v110, v92, v93
	v_cvt_pk_bf16_f32 v111, v94, v95
	s_nop 1
	v_permlane32_swap_b32_e32 v235, v236
	v_permlane32_swap_b32_e32 v96, v98
	v_permlane32_swap_b32_e32 v97, v99
	v_permlane32_swap_b32_e32 v100, v102
	v_permlane32_swap_b32_e32 v101, v103
	v_permlane32_swap_b32_e32 v104, v106
	v_permlane32_swap_b32_e32 v105, v107
	v_permlane32_swap_b32_e32 v108, v110
	v_permlane32_swap_b32_e32 v109, v111
	v_cndmask_b32_e64 v194, 0, 1, s[14:15]
	v_cmp_ne_u32_e64 s[42:43], 1, v194
	s_andn2_b64 vcc, exec, s[14:15]
	s_cbranch_vccnz .LBB0_361
